# hand-written norm1 phase (2 rows in flight, DPP reduce) + attention slc PV LDS read pipelining + bias1 loop
# baseline (speedup 1.0000x reference)
; #define TID_FROM_WV(wv) int tid = (wv) * 64 + lane_id_(); asm volatile("" : "+v"(tid));
; DI void norm_phase(const int wv, const float* xin, const float* gvec, const float* sh, const float* sc, bf16_t* hout) {
;     TID_FROM_WV(wv)
;     const int lane = tid & 63, wave = tid >> 6, gw = blockIdx.x * 8 + wave;
;     static_assert(GRID * 8 * 8 == M, "each wave owns 8 consecutive rows of one batch");
;     const int b = gw >> 9, r0 = gw * 8;
;     f32x4 gp[8], hh[8];
; #pragma unroll
;     for (int j = 0; j < 8; ++j) { const int col = 4 * lane + 256 * j;
;         gp[j] = *(const f32x4*)(gvec + col) * (*(const f32x4*)(sc + (size_t)b * MODW + col) + 1.f); hh[j] = *(const f32x4*)(sh + (size_t)b * MODW + col); }
;     f32x4 v[8], vn[8];
;     { const f32x4* xr = (const f32x4*)(xin + (size_t)r0 * D) + lane;
; #pragma unroll
;       for (int j = 0; j < 8; ++j) v[j] = xr[64 * j]; }
; #pragma unroll
;     for (int k = 0; k < 8; ++k) {
;         const int m = r0 + k;
;         if (k < 7) { const f32x4* xr = (const f32x4*)(xin + (size_t)(m + 1) * D) + lane;
; #pragma unroll
;             for (int j = 0; j < 8; ++j) vn[j] = xr[64 * j]; }
.LBB0_213:
	s_lshl_b32 s29, s16, 3
	s_or_b32 s2, s29, 1
	s_cmp_le_i32 s60, s2
	s_cselect_b64 s[0:1], -1, 0
	s_cmp_lt_i32 s2, s61
	s_cselect_b64 s[2:3], -1, 0
	s_and_b64 s[0:1], s[0:1], s[2:3]
	v_writelane_b32 v254, s29, 59
	s_andn2_b64 vcc, exec, s[0:1]
	s_mul_i32 s10, s16, 0xc000
	v_writelane_b32 v254, s16, 60
	s_cbranch_vccnz .LBB0_215
	s_mov_b64 s[2:3], s[58:59]
	s_lshl_b32 s86, s16, 12
	v_readlane_b32 s20, v253, 8
	v_readlane_b32 s21, v253, 9
	v_readlane_b32 s8, v253, 24
	v_readlane_b32 s12, v253, 0
	v_readlane_b32 s13, v253, 1
	s_lshl_b64 s[4:5], s[86:87], 2
	s_mov_b32 s11, s87
	s_lshl_b64 s[24:25], s[10:11], 2
	s_nop 3
	s_add_u32 s4, s20, s4
	s_addc_u32 s5, s21, s5
	s_add_u32 s24, s2, s24
	s_addc_u32 s25, s3, s25
	s_lshr_b32 s14, s64, 6
	s_add_u32 s8, s8, s14
	s_lshr_b32 s14, s8, 9
	s_mul_i32 s14, s14, 0xc000
	s_add_u32 s24, s24, s14
	s_addc_u32 s25, s25, 0
	s_add_u32 s22, s24, 0x2000
	s_addc_u32 s23, s25, 0
	s_lshl_b32 s14, s8, 16
	s_add_u32 s12, s12, s14
	s_addc_u32 s13, s13, 0
	s_lshl_b32 s14, s8, 15
	s_add_u32 s18, s2, 0xbb00000
	s_addc_u32 s19, s3, 0
	s_add_u32 s18, s18, s14
	s_addc_u32 s19, s19, 0
	v_mbcnt_lo_u32_b32 v149, -1, 0
	v_mbcnt_hi_u32_b32 v149, -1, v149
	v_lshlrev_b32_e32 v151, 3, v149
	v_lshlrev_b32_e32 v149, 4, v149
	v_add_u32_e32 v150, 0x1000, v149
	v_mov_b32_e32 v148, 0x358637bd
	s_mov_b32 s6, 0x3a000000
	global_load_dwordx4 v[64:67], v149, s[4:5]
	global_load_dwordx4 v[68:71], v149, s[4:5] offset:1024
	global_load_dwordx4 v[72:75], v149, s[4:5] offset:2048
	global_load_dwordx4 v[76:79], v149, s[4:5] offset:3072
	global_load_dwordx4 v[80:83], v150, s[4:5]
	global_load_dwordx4 v[84:87], v150, s[4:5] offset:1024
	global_load_dwordx4 v[88:91], v150, s[4:5] offset:2048
	global_load_dwordx4 v[92:95], v150, s[4:5] offset:3072
	global_load_dwordx4 v[32:35], v149, s[22:23]
	global_load_dwordx4 v[36:39], v149, s[22:23] offset:1024
	global_load_dwordx4 v[40:43], v149, s[22:23] offset:2048
	global_load_dwordx4 v[44:47], v149, s[22:23] offset:3072
	global_load_dwordx4 v[48:51], v150, s[22:23]
	global_load_dwordx4 v[52:55], v150, s[22:23] offset:1024
	global_load_dwordx4 v[56:59], v150, s[22:23] offset:2048
	global_load_dwordx4 v[60:63], v150, s[22:23] offset:3072
	global_load_dwordx4 v[96:99], v149, s[24:25]
	global_load_dwordx4 v[100:103], v149, s[24:25] offset:1024
	global_load_dwordx4 v[104:107], v149, s[24:25] offset:2048
	global_load_dwordx4 v[108:111], v149, s[24:25] offset:3072
	global_load_dwordx4 v[112:115], v150, s[24:25]
	global_load_dwordx4 v[116:119], v150, s[24:25] offset:1024
	global_load_dwordx4 v[120:123], v150, s[24:25] offset:2048
	global_load_dwordx4 v[124:127], v150, s[24:25] offset:3072
	global_load_dwordx4 v[0:3], v149, s[12:13]
	global_load_dwordx4 v[4:7], v149, s[12:13] offset:1024
	global_load_dwordx4 v[8:11], v149, s[12:13] offset:2048
	global_load_dwordx4 v[12:15], v149, s[12:13] offset:3072
	global_load_dwordx4 v[16:19], v150, s[12:13]
	global_load_dwordx4 v[20:23], v150, s[12:13] offset:1024
	global_load_dwordx4 v[24:27], v150, s[12:13] offset:2048
	global_load_dwordx4 v[28:31], v150, s[12:13] offset:3072
	s_add_u32 s12, s12, 0x2000
	s_addc_u32 s13, s13, 0
	s_waitcnt vmcnt(16)
	v_pk_add_f32 v[32:33], v[32:33], 1.0 op_sel_hi:[1,0]
	v_pk_add_f32 v[34:35], v[34:35], 1.0 op_sel_hi:[1,0]
	v_pk_add_f32 v[36:37], v[36:37], 1.0 op_sel_hi:[1,0]
	v_pk_add_f32 v[38:39], v[38:39], 1.0 op_sel_hi:[1,0]
	v_pk_add_f32 v[40:41], v[40:41], 1.0 op_sel_hi:[1,0]
	v_pk_add_f32 v[42:43], v[42:43], 1.0 op_sel_hi:[1,0]
	v_pk_add_f32 v[44:45], v[44:45], 1.0 op_sel_hi:[1,0]
	v_pk_add_f32 v[46:47], v[46:47], 1.0 op_sel_hi:[1,0]
	v_pk_add_f32 v[48:49], v[48:49], 1.0 op_sel_hi:[1,0]
	v_pk_add_f32 v[50:51], v[50:51], 1.0 op_sel_hi:[1,0]
	v_pk_add_f32 v[52:53], v[52:53], 1.0 op_sel_hi:[1,0]
	v_pk_add_f32 v[54:55], v[54:55], 1.0 op_sel_hi:[1,0]
	v_pk_add_f32 v[56:57], v[56:57], 1.0 op_sel_hi:[1,0]
	v_pk_add_f32 v[58:59], v[58:59], 1.0 op_sel_hi:[1,0]
	v_pk_add_f32 v[60:61], v[60:61], 1.0 op_sel_hi:[1,0]
	v_pk_add_f32 v[62:63], v[62:63], 1.0 op_sel_hi:[1,0]
	v_pk_mul_f32 v[64:65], v[64:65], v[32:33]
	v_pk_mul_f32 v[66:67], v[66:67], v[34:35]
	v_pk_mul_f32 v[68:69], v[68:69], v[36:37]
	v_pk_mul_f32 v[70:71], v[70:71], v[38:39]
	v_pk_mul_f32 v[72:73], v[72:73], v[40:41]
	v_pk_mul_f32 v[74:75], v[74:75], v[42:43]
	v_pk_mul_f32 v[76:77], v[76:77], v[44:45]
	v_pk_mul_f32 v[78:79], v[78:79], v[46:47]
	v_pk_mul_f32 v[80:81], v[80:81], v[48:49]
	v_pk_mul_f32 v[82:83], v[82:83], v[50:51]
	v_pk_mul_f32 v[84:85], v[84:85], v[52:53]
	v_pk_mul_f32 v[86:87], v[86:87], v[54:55]
	v_pk_mul_f32 v[88:89], v[88:89], v[56:57]
	v_pk_mul_f32 v[90:91], v[90:91], v[58:59]
	v_pk_mul_f32 v[92:93], v[92:93], v[60:61]
	v_pk_mul_f32 v[94:95], v[94:95], v[62:63]
	global_load_dwordx4 v[32:35], v149, s[12:13]
	global_load_dwordx4 v[36:39], v149, s[12:13] offset:1024
	global_load_dwordx4 v[40:43], v149, s[12:13] offset:2048
	global_load_dwordx4 v[44:47], v149, s[12:13] offset:3072
	global_load_dwordx4 v[48:51], v150, s[12:13]
	global_load_dwordx4 v[52:55], v150, s[12:13] offset:1024
	global_load_dwordx4 v[56:59], v150, s[12:13] offset:2048
	global_load_dwordx4 v[60:63], v150, s[12:13] offset:3072
	s_add_u32 s12, s12, 0x2000
	s_addc_u32 s13, s13, 0
	s_waitcnt vmcnt(8)
; DI unsigned pk2(float lo, float hi) { f32x2 v = {lo, hi}; bf16x2n b = __builtin_convertvector(v, bf16x2n); return __builtin_bit_cast(unsigned, b); }
; DI void norm_phase(const int wv, const float* xin, const float* gvec, const float* sh, const float* sc, bf16_t* hout) {
;     ...
;         float s = 0.f;
; #pragma unroll
;         for (int j = 0; j < 8; ++j) s += (v[j].x * v[j].x + v[j].y * v[j].y) + (v[j].z * v[j].z + v[j].w * v[j].w);
; #pragma unroll
;         for (int o = 1; o < 64; o <<= 1) s += __shfl_xor(s, o);
;         const float rstd = rsqrtf(s * (1.f / D) + 1e-6f);
;         u32x2* o8 = (u32x2*)(hout + (size_t)m * D) + lane;
; #pragma unroll
;         for (int j = 0; j < 8; ++j) { const f32x4 y = v[j] * rstd * gp[j] + hh[j];
;             u32x2 w; w.x = pk2(y.x, y.y); w.y = pk2(y.z, y.w); o8[64 * j] = w; }
; #pragma unroll
;         for (int j = 0; j < 8; ++j) v[j] = vn[j];
;     }
	v_pk_mul_f32 v[152:153], v[0:1], v[0:1]
	v_pk_fma_f32 v[152:153], v[2:3], v[2:3], v[152:153]
	v_pk_fma_f32 v[152:153], v[4:5], v[4:5], v[152:153]
	v_pk_fma_f32 v[152:153], v[6:7], v[6:7], v[152:153]
	v_pk_fma_f32 v[152:153], v[8:9], v[8:9], v[152:153]
	v_pk_fma_f32 v[152:153], v[10:11], v[10:11], v[152:153]
	v_pk_fma_f32 v[152:153], v[12:13], v[12:13], v[152:153]
	v_pk_fma_f32 v[152:153], v[14:15], v[14:15], v[152:153]
	v_pk_fma_f32 v[152:153], v[16:17], v[16:17], v[152:153]
	v_pk_fma_f32 v[152:153], v[18:19], v[18:19], v[152:153]
	v_pk_fma_f32 v[152:153], v[20:21], v[20:21], v[152:153]
	v_pk_fma_f32 v[152:153], v[22:23], v[22:23], v[152:153]
	v_pk_fma_f32 v[152:153], v[24:25], v[24:25], v[152:153]
	v_pk_fma_f32 v[152:153], v[26:27], v[26:27], v[152:153]
	v_pk_fma_f32 v[152:153], v[28:29], v[28:29], v[152:153]
	v_pk_fma_f32 v[152:153], v[30:31], v[30:31], v[152:153]
	s_nop 0
	v_add_f32_e32 v144, v152, v153
	s_nop 1
	v_add_f32_dpp v144, v144, v144 quad_perm:[1,0,3,2] row_mask:0xf bank_mask:0xf
	s_nop 1
	v_add_f32_dpp v144, v144, v144 quad_perm:[2,3,0,1] row_mask:0xf bank_mask:0xf
	s_nop 1
	v_add_f32_dpp v144, v144, v144 row_half_mirror row_mask:0xf bank_mask:0xf
	s_nop 1
	v_add_f32_dpp v144, v144, v144 row_mirror row_mask:0xf bank_mask:0xf
	s_nop 0
	v_mov_b32_e32 v145, v144
	s_nop 1
	v_permlane16_swap_b32_e32 v145, v144
	s_nop 0
	v_add_f32_e32 v144, v144, v145
	v_mov_b32_e32 v145, v144
	s_nop 1
	v_permlane32_swap_b32_e32 v145, v144
	s_nop 0
	v_add_f32_e32 v144, v144, v145
	v_fma_f32 v146, v144, s6, v148
	v_rsq_f32_e32 v146, v146
	s_nop 0
	v_mov_b32_e32 v147, v146
	v_pk_mul_f32 v[0:1], v[0:1], v[146:147]
	v_pk_mul_f32 v[2:3], v[2:3], v[146:147]
	v_pk_mul_f32 v[4:5], v[4:5], v[146:147]
	v_pk_mul_f32 v[6:7], v[6:7], v[146:147]
	v_pk_mul_f32 v[8:9], v[8:9], v[146:147]
	v_pk_mul_f32 v[10:11], v[10:11], v[146:147]
	v_pk_mul_f32 v[12:13], v[12:13], v[146:147]
	v_pk_mul_f32 v[14:15], v[14:15], v[146:147]
	v_pk_mul_f32 v[16:17], v[16:17], v[146:147]
	v_pk_mul_f32 v[18:19], v[18:19], v[146:147]
	v_pk_mul_f32 v[20:21], v[20:21], v[146:147]
	v_pk_mul_f32 v[22:23], v[22:23], v[146:147]
	v_pk_mul_f32 v[24:25], v[24:25], v[146:147]
	v_pk_mul_f32 v[26:27], v[26:27], v[146:147]
	v_pk_mul_f32 v[28:29], v[28:29], v[146:147]
	v_pk_mul_f32 v[30:31], v[30:31], v[146:147]
	v_pk_fma_f32 v[0:1], v[0:1], v[64:65], v[96:97]
	v_pk_fma_f32 v[2:3], v[2:3], v[66:67], v[98:99]
	v_pk_fma_f32 v[4:5], v[4:5], v[68:69], v[100:101]
	v_pk_fma_f32 v[6:7], v[6:7], v[70:71], v[102:103]
	v_pk_fma_f32 v[8:9], v[8:9], v[72:73], v[104:105]
	v_pk_fma_f32 v[10:11], v[10:11], v[74:75], v[106:107]
	v_pk_fma_f32 v[12:13], v[12:13], v[76:77], v[108:109]
	v_pk_fma_f32 v[14:15], v[14:15], v[78:79], v[110:111]
	v_pk_fma_f32 v[16:17], v[16:17], v[80:81], v[112:113]
	v_pk_fma_f32 v[18:19], v[18:19], v[82:83], v[114:115]
	v_pk_fma_f32 v[20:21], v[20:21], v[84:85], v[116:117]
	v_pk_fma_f32 v[22:23], v[22:23], v[86:87], v[118:119]
	v_pk_fma_f32 v[24:25], v[24:25], v[88:89], v[120:121]
	v_pk_fma_f32 v[26:27], v[26:27], v[90:91], v[122:123]
	v_pk_fma_f32 v[28:29], v[28:29], v[92:93], v[124:125]
	v_pk_fma_f32 v[30:31], v[30:31], v[94:95], v[126:127]
	v_cvt_pk_bf16_f32 v128, v0, v1
	v_cvt_pk_bf16_f32 v129, v2, v3
	v_cvt_pk_bf16_f32 v130, v4, v5
	v_cvt_pk_bf16_f32 v131, v6, v7
	v_cvt_pk_bf16_f32 v132, v8, v9
	v_cvt_pk_bf16_f32 v133, v10, v11
	v_cvt_pk_bf16_f32 v134, v12, v13
	v_cvt_pk_bf16_f32 v135, v14, v15
	v_cvt_pk_bf16_f32 v136, v16, v17
	v_cvt_pk_bf16_f32 v137, v18, v19
	v_cvt_pk_bf16_f32 v138, v20, v21
	v_cvt_pk_bf16_f32 v139, v22, v23
	v_cvt_pk_bf16_f32 v140, v24, v25
	v_cvt_pk_bf16_f32 v141, v26, v27
	v_cvt_pk_bf16_f32 v142, v28, v29
	v_cvt_pk_bf16_f32 v143, v30, v31
	global_store_dwordx2 v151, v[128:129], s[18:19]
	global_store_dwordx2 v151, v[130:131], s[18:19] offset:512
	global_store_dwordx2 v151, v[132:133], s[18:19] offset:1024
	global_store_dwordx2 v151, v[134:135], s[18:19] offset:1536
	global_store_dwordx2 v151, v[136:137], s[18:19] offset:2048
	global_store_dwordx2 v151, v[138:139], s[18:19] offset:2560
	global_store_dwordx2 v151, v[140:141], s[18:19] offset:3072
	global_store_dwordx2 v151, v[142:143], s[18:19] offset:3584
	s_add_u32 s18, s18, 0x1000
	s_addc_u32 s19, s19, 0
	global_load_dwordx4 v[0:3], v149, s[12:13]
	global_load_dwordx4 v[4:7], v149, s[12:13] offset:1024
	global_load_dwordx4 v[8:11], v149, s[12:13] offset:2048
	global_load_dwordx4 v[12:15], v149, s[12:13] offset:3072
	global_load_dwordx4 v[16:19], v150, s[12:13]
	global_load_dwordx4 v[20:23], v150, s[12:13] offset:1024
	global_load_dwordx4 v[24:27], v150, s[12:13] offset:2048
	global_load_dwordx4 v[28:31], v150, s[12:13] offset:3072
	s_add_u32 s12, s12, 0x2000
	s_addc_u32 s13, s13, 0
	s_waitcnt vmcnt(16)
; DI unsigned pk2(float lo, float hi) { f32x2 v = {lo, hi}; bf16x2n b = __builtin_convertvector(v, bf16x2n); return __builtin_bit_cast(unsigned, b); }
; DI void norm_phase(const int wv, const float* xin, const float* gvec, const float* sh, const float* sc, bf16_t* hout) {
;     ...
;         float s = 0.f;
; #pragma unroll
;         for (int j = 0; j < 8; ++j) s += (v[j].x * v[j].x + v[j].y * v[j].y) + (v[j].z * v[j].z + v[j].w * v[j].w);
; #pragma unroll
;         for (int o = 1; o < 64; o <<= 1) s += __shfl_xor(s, o);
;         const float rstd = rsqrtf(s * (1.f / D) + 1e-6f);
;         u32x2* o8 = (u32x2*)(hout + (size_t)m * D) + lane;
; #pragma unroll
;         for (int j = 0; j < 8; ++j) { const f32x4 y = v[j] * rstd * gp[j] + hh[j];
;             u32x2 w; w.x = pk2(y.x, y.y); w.y = pk2(y.z, y.w); o8[64 * j] = w; }
; #pragma unroll
;         for (int j = 0; j < 8; ++j) v[j] = vn[j];
;     }
	v_pk_mul_f32 v[152:153], v[32:33], v[32:33]
	v_pk_fma_f32 v[152:153], v[34:35], v[34:35], v[152:153]
	v_pk_fma_f32 v[152:153], v[36:37], v[36:37], v[152:153]
	v_pk_fma_f32 v[152:153], v[38:39], v[38:39], v[152:153]
	v_pk_fma_f32 v[152:153], v[40:41], v[40:41], v[152:153]
	v_pk_fma_f32 v[152:153], v[42:43], v[42:43], v[152:153]
	v_pk_fma_f32 v[152:153], v[44:45], v[44:45], v[152:153]
	v_pk_fma_f32 v[152:153], v[46:47], v[46:47], v[152:153]
	v_pk_fma_f32 v[152:153], v[48:49], v[48:49], v[152:153]
	v_pk_fma_f32 v[152:153], v[50:51], v[50:51], v[152:153]
	v_pk_fma_f32 v[152:153], v[52:53], v[52:53], v[152:153]
	v_pk_fma_f32 v[152:153], v[54:55], v[54:55], v[152:153]
	v_pk_fma_f32 v[152:153], v[56:57], v[56:57], v[152:153]
	v_pk_fma_f32 v[152:153], v[58:59], v[58:59], v[152:153]
	v_pk_fma_f32 v[152:153], v[60:61], v[60:61], v[152:153]
	v_pk_fma_f32 v[152:153], v[62:63], v[62:63], v[152:153]
	s_nop 0
	v_add_f32_e32 v144, v152, v153
	s_nop 1
	v_add_f32_dpp v144, v144, v144 quad_perm:[1,0,3,2] row_mask:0xf bank_mask:0xf
	s_nop 1
	v_add_f32_dpp v144, v144, v144 quad_perm:[2,3,0,1] row_mask:0xf bank_mask:0xf
	s_nop 1
	v_add_f32_dpp v144, v144, v144 row_half_mirror row_mask:0xf bank_mask:0xf
	s_nop 1
	v_add_f32_dpp v144, v144, v144 row_mirror row_mask:0xf bank_mask:0xf
	s_nop 0
	v_mov_b32_e32 v145, v144
	s_nop 1
	v_permlane16_swap_b32_e32 v145, v144
	s_nop 0
	v_add_f32_e32 v144, v144, v145
	v_mov_b32_e32 v145, v144
	s_nop 1
	v_permlane32_swap_b32_e32 v145, v144
	s_nop 0
	v_add_f32_e32 v144, v144, v145
	v_fma_f32 v146, v144, s6, v148
	v_rsq_f32_e32 v146, v146
	s_nop 0
	v_mov_b32_e32 v147, v146
	v_pk_mul_f32 v[32:33], v[32:33], v[146:147]
	v_pk_mul_f32 v[34:35], v[34:35], v[146:147]
	v_pk_mul_f32 v[36:37], v[36:37], v[146:147]
	v_pk_mul_f32 v[38:39], v[38:39], v[146:147]
	v_pk_mul_f32 v[40:41], v[40:41], v[146:147]
	v_pk_mul_f32 v[42:43], v[42:43], v[146:147]
	v_pk_mul_f32 v[44:45], v[44:45], v[146:147]
	v_pk_mul_f32 v[46:47], v[46:47], v[146:147]
	v_pk_mul_f32 v[48:49], v[48:49], v[146:147]
	v_pk_mul_f32 v[50:51], v[50:51], v[146:147]
	v_pk_mul_f32 v[52:53], v[52:53], v[146:147]
	v_pk_mul_f32 v[54:55], v[54:55], v[146:147]
	v_pk_mul_f32 v[56:57], v[56:57], v[146:147]
	v_pk_mul_f32 v[58:59], v[58:59], v[146:147]
	v_pk_mul_f32 v[60:61], v[60:61], v[146:147]
	v_pk_mul_f32 v[62:63], v[62:63], v[146:147]
	v_pk_fma_f32 v[32:33], v[32:33], v[64:65], v[96:97]
	v_pk_fma_f32 v[34:35], v[34:35], v[66:67], v[98:99]
	v_pk_fma_f32 v[36:37], v[36:37], v[68:69], v[100:101]
	v_pk_fma_f32 v[38:39], v[38:39], v[70:71], v[102:103]
	v_pk_fma_f32 v[40:41], v[40:41], v[72:73], v[104:105]
	v_pk_fma_f32 v[42:43], v[42:43], v[74:75], v[106:107]
	v_pk_fma_f32 v[44:45], v[44:45], v[76:77], v[108:109]
	v_pk_fma_f32 v[46:47], v[46:47], v[78:79], v[110:111]
	v_pk_fma_f32 v[48:49], v[48:49], v[80:81], v[112:113]
	v_pk_fma_f32 v[50:51], v[50:51], v[82:83], v[114:115]
	v_pk_fma_f32 v[52:53], v[52:53], v[84:85], v[116:117]
	v_pk_fma_f32 v[54:55], v[54:55], v[86:87], v[118:119]
	v_pk_fma_f32 v[56:57], v[56:57], v[88:89], v[120:121]
	v_pk_fma_f32 v[58:59], v[58:59], v[90:91], v[122:123]
	v_pk_fma_f32 v[60:61], v[60:61], v[92:93], v[124:125]
	v_pk_fma_f32 v[62:63], v[62:63], v[94:95], v[126:127]
	v_cvt_pk_bf16_f32 v128, v32, v33
	v_cvt_pk_bf16_f32 v129, v34, v35
	v_cvt_pk_bf16_f32 v130, v36, v37
	v_cvt_pk_bf16_f32 v131, v38, v39
	v_cvt_pk_bf16_f32 v132, v40, v41
	v_cvt_pk_bf16_f32 v133, v42, v43
	v_cvt_pk_bf16_f32 v134, v44, v45
	v_cvt_pk_bf16_f32 v135, v46, v47
	v_cvt_pk_bf16_f32 v136, v48, v49
	v_cvt_pk_bf16_f32 v137, v50, v51
	v_cvt_pk_bf16_f32 v138, v52, v53
	v_cvt_pk_bf16_f32 v139, v54, v55
	v_cvt_pk_bf16_f32 v140, v56, v57
	v_cvt_pk_bf16_f32 v141, v58, v59
	v_cvt_pk_bf16_f32 v142, v60, v61
	v_cvt_pk_bf16_f32 v143, v62, v63
	global_store_dwordx2 v151, v[128:129], s[18:19]
	global_store_dwordx2 v151, v[130:131], s[18:19] offset:512
	global_store_dwordx2 v151, v[132:133], s[18:19] offset:1024
	global_store_dwordx2 v151, v[134:135], s[18:19] offset:1536
	global_store_dwordx2 v151, v[136:137], s[18:19] offset:2048
	global_store_dwordx2 v151, v[138:139], s[18:19] offset:2560
	global_store_dwordx2 v151, v[140:141], s[18:19] offset:3072
	global_store_dwordx2 v151, v[142:143], s[18:19] offset:3584
	s_add_u32 s18, s18, 0x1000
	s_addc_u32 s19, s19, 0
	global_load_dwordx4 v[32:35], v149, s[12:13]
	global_load_dwordx4 v[36:39], v149, s[12:13] offset:1024
	global_load_dwordx4 v[40:43], v149, s[12:13] offset:2048
	global_load_dwordx4 v[44:47], v149, s[12:13] offset:3072
	global_load_dwordx4 v[48:51], v150, s[12:13]
	global_load_dwordx4 v[52:55], v150, s[12:13] offset:1024
	global_load_dwordx4 v[56:59], v150, s[12:13] offset:2048
	global_load_dwordx4 v[60:63], v150, s[12:13] offset:3072
	s_add_u32 s12, s12, 0x2000
	s_addc_u32 s13, s13, 0
	s_waitcnt vmcnt(16)
; DI unsigned pk2(float lo, float hi) { f32x2 v = {lo, hi}; bf16x2n b = __builtin_convertvector(v, bf16x2n); return __builtin_bit_cast(unsigned, b); }
; DI void norm_phase(const int wv, const float* xin, const float* gvec, const float* sh, const float* sc, bf16_t* hout) {
;     ...
;         float s = 0.f;
; #pragma unroll
;         for (int j = 0; j < 8; ++j) s += (v[j].x * v[j].x + v[j].y * v[j].y) + (v[j].z * v[j].z + v[j].w * v[j].w);
; #pragma unroll
;         for (int o = 1; o < 64; o <<= 1) s += __shfl_xor(s, o);
;         const float rstd = rsqrtf(s * (1.f / D) + 1e-6f);
;         u32x2* o8 = (u32x2*)(hout + (size_t)m * D) + lane;
; #pragma unroll
;         for (int j = 0; j < 8; ++j) { const f32x4 y = v[j] * rstd * gp[j] + hh[j];
;             u32x2 w; w.x = pk2(y.x, y.y); w.y = pk2(y.z, y.w); o8[64 * j] = w; }
; #pragma unroll
;         for (int j = 0; j < 8; ++j) v[j] = vn[j];
;     }
	v_pk_mul_f32 v[152:153], v[0:1], v[0:1]
	v_pk_fma_f32 v[152:153], v[2:3], v[2:3], v[152:153]
	v_pk_fma_f32 v[152:153], v[4:5], v[4:5], v[152:153]
	v_pk_fma_f32 v[152:153], v[6:7], v[6:7], v[152:153]
	v_pk_fma_f32 v[152:153], v[8:9], v[8:9], v[152:153]
	v_pk_fma_f32 v[152:153], v[10:11], v[10:11], v[152:153]
	v_pk_fma_f32 v[152:153], v[12:13], v[12:13], v[152:153]
	v_pk_fma_f32 v[152:153], v[14:15], v[14:15], v[152:153]
	v_pk_fma_f32 v[152:153], v[16:17], v[16:17], v[152:153]
	v_pk_fma_f32 v[152:153], v[18:19], v[18:19], v[152:153]
	v_pk_fma_f32 v[152:153], v[20:21], v[20:21], v[152:153]
	v_pk_fma_f32 v[152:153], v[22:23], v[22:23], v[152:153]
	v_pk_fma_f32 v[152:153], v[24:25], v[24:25], v[152:153]
	v_pk_fma_f32 v[152:153], v[26:27], v[26:27], v[152:153]
	v_pk_fma_f32 v[152:153], v[28:29], v[28:29], v[152:153]
	v_pk_fma_f32 v[152:153], v[30:31], v[30:31], v[152:153]
	s_nop 0
	v_add_f32_e32 v144, v152, v153
	s_nop 1
	v_add_f32_dpp v144, v144, v144 quad_perm:[1,0,3,2] row_mask:0xf bank_mask:0xf
	s_nop 1
	v_add_f32_dpp v144, v144, v144 quad_perm:[2,3,0,1] row_mask:0xf bank_mask:0xf
	s_nop 1
	v_add_f32_dpp v144, v144, v144 row_half_mirror row_mask:0xf bank_mask:0xf
	s_nop 1
	v_add_f32_dpp v144, v144, v144 row_mirror row_mask:0xf bank_mask:0xf
	s_nop 0
	v_mov_b32_e32 v145, v144
	s_nop 1
	v_permlane16_swap_b32_e32 v145, v144
	s_nop 0
	v_add_f32_e32 v144, v144, v145
	v_mov_b32_e32 v145, v144
	s_nop 1
	v_permlane32_swap_b32_e32 v145, v144
	s_nop 0
	v_add_f32_e32 v144, v144, v145
	v_fma_f32 v146, v144, s6, v148
	v_rsq_f32_e32 v146, v146
	s_nop 0
	v_mov_b32_e32 v147, v146
	v_pk_mul_f32 v[0:1], v[0:1], v[146:147]
	v_pk_mul_f32 v[2:3], v[2:3], v[146:147]
	v_pk_mul_f32 v[4:5], v[4:5], v[146:147]
	v_pk_mul_f32 v[6:7], v[6:7], v[146:147]
	v_pk_mul_f32 v[8:9], v[8:9], v[146:147]
	v_pk_mul_f32 v[10:11], v[10:11], v[146:147]
	v_pk_mul_f32 v[12:13], v[12:13], v[146:147]
	v_pk_mul_f32 v[14:15], v[14:15], v[146:147]
	v_pk_mul_f32 v[16:17], v[16:17], v[146:147]
	v_pk_mul_f32 v[18:19], v[18:19], v[146:147]
	v_pk_mul_f32 v[20:21], v[20:21], v[146:147]
	v_pk_mul_f32 v[22:23], v[22:23], v[146:147]
	v_pk_mul_f32 v[24:25], v[24:25], v[146:147]
	v_pk_mul_f32 v[26:27], v[26:27], v[146:147]
	v_pk_mul_f32 v[28:29], v[28:29], v[146:147]
	v_pk_mul_f32 v[30:31], v[30:31], v[146:147]
	v_pk_fma_f32 v[0:1], v[0:1], v[64:65], v[96:97]
	v_pk_fma_f32 v[2:3], v[2:3], v[66:67], v[98:99]
	v_pk_fma_f32 v[4:5], v[4:5], v[68:69], v[100:101]
	v_pk_fma_f32 v[6:7], v[6:7], v[70:71], v[102:103]
	v_pk_fma_f32 v[8:9], v[8:9], v[72:73], v[104:105]
	v_pk_fma_f32 v[10:11], v[10:11], v[74:75], v[106:107]
	v_pk_fma_f32 v[12:13], v[12:13], v[76:77], v[108:109]
	v_pk_fma_f32 v[14:15], v[14:15], v[78:79], v[110:111]
	v_pk_fma_f32 v[16:17], v[16:17], v[80:81], v[112:113]
	v_pk_fma_f32 v[18:19], v[18:19], v[82:83], v[114:115]
	v_pk_fma_f32 v[20:21], v[20:21], v[84:85], v[116:117]
	v_pk_fma_f32 v[22:23], v[22:23], v[86:87], v[118:119]
	v_pk_fma_f32 v[24:25], v[24:25], v[88:89], v[120:121]
	v_pk_fma_f32 v[26:27], v[26:27], v[90:91], v[122:123]
	v_pk_fma_f32 v[28:29], v[28:29], v[92:93], v[124:125]
	v_pk_fma_f32 v[30:31], v[30:31], v[94:95], v[126:127]
	v_cvt_pk_bf16_f32 v128, v0, v1
	v_cvt_pk_bf16_f32 v129, v2, v3
	v_cvt_pk_bf16_f32 v130, v4, v5
	v_cvt_pk_bf16_f32 v131, v6, v7
	v_cvt_pk_bf16_f32 v132, v8, v9
	v_cvt_pk_bf16_f32 v133, v10, v11
	v_cvt_pk_bf16_f32 v134, v12, v13
	v_cvt_pk_bf16_f32 v135, v14, v15
	v_cvt_pk_bf16_f32 v136, v16, v17
	v_cvt_pk_bf16_f32 v137, v18, v19
	v_cvt_pk_bf16_f32 v138, v20, v21
	v_cvt_pk_bf16_f32 v139, v22, v23
	v_cvt_pk_bf16_f32 v140, v24, v25
	v_cvt_pk_bf16_f32 v141, v26, v27
	v_cvt_pk_bf16_f32 v142, v28, v29
	v_cvt_pk_bf16_f32 v143, v30, v31
	global_store_dwordx2 v151, v[128:129], s[18:19]
	global_store_dwordx2 v151, v[130:131], s[18:19] offset:512
	global_store_dwordx2 v151, v[132:133], s[18:19] offset:1024
	global_store_dwordx2 v151, v[134:135], s[18:19] offset:1536
	global_store_dwordx2 v151, v[136:137], s[18:19] offset:2048
	global_store_dwordx2 v151, v[138:139], s[18:19] offset:2560
	global_store_dwordx2 v151, v[140:141], s[18:19] offset:3072
	global_store_dwordx2 v151, v[142:143], s[18:19] offset:3584
	s_add_u32 s18, s18, 0x1000
	s_addc_u32 s19, s19, 0
	global_load_dwordx4 v[0:3], v149, s[12:13]
	global_load_dwordx4 v[4:7], v149, s[12:13] offset:1024
	global_load_dwordx4 v[8:11], v149, s[12:13] offset:2048
	global_load_dwordx4 v[12:15], v149, s[12:13] offset:3072
	global_load_dwordx4 v[16:19], v150, s[12:13]
	global_load_dwordx4 v[20:23], v150, s[12:13] offset:1024
	global_load_dwordx4 v[24:27], v150, s[12:13] offset:2048
	global_load_dwordx4 v[28:31], v150, s[12:13] offset:3072
	s_add_u32 s12, s12, 0x2000
	s_addc_u32 s13, s13, 0
	s_waitcnt vmcnt(16)
; DI unsigned pk2(float lo, float hi) { f32x2 v = {lo, hi}; bf16x2n b = __builtin_convertvector(v, bf16x2n); return __builtin_bit_cast(unsigned, b); }
; DI void norm_phase(const int wv, const float* xin, const float* gvec, const float* sh, const float* sc, bf16_t* hout) {
;     ...
;         float s = 0.f;
; #pragma unroll
;         for (int j = 0; j < 8; ++j) s += (v[j].x * v[j].x + v[j].y * v[j].y) + (v[j].z * v[j].z + v[j].w * v[j].w);
; #pragma unroll
;         for (int o = 1; o < 64; o <<= 1) s += __shfl_xor(s, o);
;         const float rstd = rsqrtf(s * (1.f / D) + 1e-6f);
;         u32x2* o8 = (u32x2*)(hout + (size_t)m * D) + lane;
; #pragma unroll
;         for (int j = 0; j < 8; ++j) { const f32x4 y = v[j] * rstd * gp[j] + hh[j];
;             u32x2 w; w.x = pk2(y.x, y.y); w.y = pk2(y.z, y.w); o8[64 * j] = w; }
; #pragma unroll
;         for (int j = 0; j < 8; ++j) v[j] = vn[j];
;     }
	v_pk_mul_f32 v[152:153], v[32:33], v[32:33]
	v_pk_fma_f32 v[152:153], v[34:35], v[34:35], v[152:153]
	v_pk_fma_f32 v[152:153], v[36:37], v[36:37], v[152:153]
	v_pk_fma_f32 v[152:153], v[38:39], v[38:39], v[152:153]
	v_pk_fma_f32 v[152:153], v[40:41], v[40:41], v[152:153]
	v_pk_fma_f32 v[152:153], v[42:43], v[42:43], v[152:153]
	v_pk_fma_f32 v[152:153], v[44:45], v[44:45], v[152:153]
	v_pk_fma_f32 v[152:153], v[46:47], v[46:47], v[152:153]
	v_pk_fma_f32 v[152:153], v[48:49], v[48:49], v[152:153]
	v_pk_fma_f32 v[152:153], v[50:51], v[50:51], v[152:153]
	v_pk_fma_f32 v[152:153], v[52:53], v[52:53], v[152:153]
	v_pk_fma_f32 v[152:153], v[54:55], v[54:55], v[152:153]
	v_pk_fma_f32 v[152:153], v[56:57], v[56:57], v[152:153]
	v_pk_fma_f32 v[152:153], v[58:59], v[58:59], v[152:153]
	v_pk_fma_f32 v[152:153], v[60:61], v[60:61], v[152:153]
	v_pk_fma_f32 v[152:153], v[62:63], v[62:63], v[152:153]
	s_nop 0
	v_add_f32_e32 v144, v152, v153
	s_nop 1
	v_add_f32_dpp v144, v144, v144 quad_perm:[1,0,3,2] row_mask:0xf bank_mask:0xf
	s_nop 1
	v_add_f32_dpp v144, v144, v144 quad_perm:[2,3,0,1] row_mask:0xf bank_mask:0xf
	s_nop 1
	v_add_f32_dpp v144, v144, v144 row_half_mirror row_mask:0xf bank_mask:0xf
	s_nop 1
	v_add_f32_dpp v144, v144, v144 row_mirror row_mask:0xf bank_mask:0xf
	s_nop 0
	v_mov_b32_e32 v145, v144
	s_nop 1
	v_permlane16_swap_b32_e32 v145, v144
	s_nop 0
	v_add_f32_e32 v144, v144, v145
	v_mov_b32_e32 v145, v144
	s_nop 1
	v_permlane32_swap_b32_e32 v145, v144
	s_nop 0
	v_add_f32_e32 v144, v144, v145
	v_fma_f32 v146, v144, s6, v148
	v_rsq_f32_e32 v146, v146
	s_nop 0
	v_mov_b32_e32 v147, v146
	v_pk_mul_f32 v[32:33], v[32:33], v[146:147]
	v_pk_mul_f32 v[34:35], v[34:35], v[146:147]
	v_pk_mul_f32 v[36:37], v[36:37], v[146:147]
	v_pk_mul_f32 v[38:39], v[38:39], v[146:147]
	v_pk_mul_f32 v[40:41], v[40:41], v[146:147]
	v_pk_mul_f32 v[42:43], v[42:43], v[146:147]
	v_pk_mul_f32 v[44:45], v[44:45], v[146:147]
	v_pk_mul_f32 v[46:47], v[46:47], v[146:147]
	v_pk_mul_f32 v[48:49], v[48:49], v[146:147]
	v_pk_mul_f32 v[50:51], v[50:51], v[146:147]
	v_pk_mul_f32 v[52:53], v[52:53], v[146:147]
	v_pk_mul_f32 v[54:55], v[54:55], v[146:147]
	v_pk_mul_f32 v[56:57], v[56:57], v[146:147]
	v_pk_mul_f32 v[58:59], v[58:59], v[146:147]
	v_pk_mul_f32 v[60:61], v[60:61], v[146:147]
	v_pk_mul_f32 v[62:63], v[62:63], v[146:147]
	v_pk_fma_f32 v[32:33], v[32:33], v[64:65], v[96:97]
	v_pk_fma_f32 v[34:35], v[34:35], v[66:67], v[98:99]
	v_pk_fma_f32 v[36:37], v[36:37], v[68:69], v[100:101]
	v_pk_fma_f32 v[38:39], v[38:39], v[70:71], v[102:103]
	v_pk_fma_f32 v[40:41], v[40:41], v[72:73], v[104:105]
	v_pk_fma_f32 v[42:43], v[42:43], v[74:75], v[106:107]
	v_pk_fma_f32 v[44:45], v[44:45], v[76:77], v[108:109]
	v_pk_fma_f32 v[46:47], v[46:47], v[78:79], v[110:111]
	v_pk_fma_f32 v[48:49], v[48:49], v[80:81], v[112:113]
	v_pk_fma_f32 v[50:51], v[50:51], v[82:83], v[114:115]
	v_pk_fma_f32 v[52:53], v[52:53], v[84:85], v[116:117]
	v_pk_fma_f32 v[54:55], v[54:55], v[86:87], v[118:119]
	v_pk_fma_f32 v[56:57], v[56:57], v[88:89], v[120:121]
	v_pk_fma_f32 v[58:59], v[58:59], v[90:91], v[122:123]
	v_pk_fma_f32 v[60:61], v[60:61], v[92:93], v[124:125]
	v_pk_fma_f32 v[62:63], v[62:63], v[94:95], v[126:127]
	v_cvt_pk_bf16_f32 v128, v32, v33
	v_cvt_pk_bf16_f32 v129, v34, v35
	v_cvt_pk_bf16_f32 v130, v36, v37
	v_cvt_pk_bf16_f32 v131, v38, v39
	v_cvt_pk_bf16_f32 v132, v40, v41
	v_cvt_pk_bf16_f32 v133, v42, v43
	v_cvt_pk_bf16_f32 v134, v44, v45
	v_cvt_pk_bf16_f32 v135, v46, v47
	v_cvt_pk_bf16_f32 v136, v48, v49
	v_cvt_pk_bf16_f32 v137, v50, v51
	v_cvt_pk_bf16_f32 v138, v52, v53
	v_cvt_pk_bf16_f32 v139, v54, v55
	v_cvt_pk_bf16_f32 v140, v56, v57
	v_cvt_pk_bf16_f32 v141, v58, v59
	v_cvt_pk_bf16_f32 v142, v60, v61
	v_cvt_pk_bf16_f32 v143, v62, v63
	global_store_dwordx2 v151, v[128:129], s[18:19]
	global_store_dwordx2 v151, v[130:131], s[18:19] offset:512
	global_store_dwordx2 v151, v[132:133], s[18:19] offset:1024
	global_store_dwordx2 v151, v[134:135], s[18:19] offset:1536
	global_store_dwordx2 v151, v[136:137], s[18:19] offset:2048
	global_store_dwordx2 v151, v[138:139], s[18:19] offset:2560
	global_store_dwordx2 v151, v[140:141], s[18:19] offset:3072
	global_store_dwordx2 v151, v[142:143], s[18:19] offset:3584
	s_add_u32 s18, s18, 0x1000
	s_addc_u32 s19, s19, 0
	global_load_dwordx4 v[32:35], v149, s[12:13]
	global_load_dwordx4 v[36:39], v149, s[12:13] offset:1024
	global_load_dwordx4 v[40:43], v149, s[12:13] offset:2048
	global_load_dwordx4 v[44:47], v149, s[12:13] offset:3072
	global_load_dwordx4 v[48:51], v150, s[12:13]
	global_load_dwordx4 v[52:55], v150, s[12:13] offset:1024
	global_load_dwordx4 v[56:59], v150, s[12:13] offset:2048
	global_load_dwordx4 v[60:63], v150, s[12:13] offset:3072
	s_add_u32 s12, s12, 0x2000
	s_addc_u32 s13, s13, 0
	s_waitcnt vmcnt(16)
; DI unsigned pk2(float lo, float hi) { f32x2 v = {lo, hi}; bf16x2n b = __builtin_convertvector(v, bf16x2n); return __builtin_bit_cast(unsigned, b); }
; DI void norm_phase(const int wv, const float* xin, const float* gvec, const float* sh, const float* sc, bf16_t* hout) {
;     ...
;         float s = 0.f;
; #pragma unroll
;         for (int j = 0; j < 8; ++j) s += (v[j].x * v[j].x + v[j].y * v[j].y) + (v[j].z * v[j].z + v[j].w * v[j].w);
; #pragma unroll
;         for (int o = 1; o < 64; o <<= 1) s += __shfl_xor(s, o);
;         const float rstd = rsqrtf(s * (1.f / D) + 1e-6f);
;         u32x2* o8 = (u32x2*)(hout + (size_t)m * D) + lane;
; #pragma unroll
;         for (int j = 0; j < 8; ++j) { const f32x4 y = v[j] * rstd * gp[j] + hh[j];
;             u32x2 w; w.x = pk2(y.x, y.y); w.y = pk2(y.z, y.w); o8[64 * j] = w; }
; #pragma unroll
;         for (int j = 0; j < 8; ++j) v[j] = vn[j];
;     }
	v_pk_mul_f32 v[152:153], v[0:1], v[0:1]
	v_pk_fma_f32 v[152:153], v[2:3], v[2:3], v[152:153]
	v_pk_fma_f32 v[152:153], v[4:5], v[4:5], v[152:153]
	v_pk_fma_f32 v[152:153], v[6:7], v[6:7], v[152:153]
	v_pk_fma_f32 v[152:153], v[8:9], v[8:9], v[152:153]
	v_pk_fma_f32 v[152:153], v[10:11], v[10:11], v[152:153]
	v_pk_fma_f32 v[152:153], v[12:13], v[12:13], v[152:153]
	v_pk_fma_f32 v[152:153], v[14:15], v[14:15], v[152:153]
	v_pk_fma_f32 v[152:153], v[16:17], v[16:17], v[152:153]
	v_pk_fma_f32 v[152:153], v[18:19], v[18:19], v[152:153]
	v_pk_fma_f32 v[152:153], v[20:21], v[20:21], v[152:153]
	v_pk_fma_f32 v[152:153], v[22:23], v[22:23], v[152:153]
	v_pk_fma_f32 v[152:153], v[24:25], v[24:25], v[152:153]
	v_pk_fma_f32 v[152:153], v[26:27], v[26:27], v[152:153]
	v_pk_fma_f32 v[152:153], v[28:29], v[28:29], v[152:153]
	v_pk_fma_f32 v[152:153], v[30:31], v[30:31], v[152:153]
	s_nop 0
	v_add_f32_e32 v144, v152, v153
	s_nop 1
	v_add_f32_dpp v144, v144, v144 quad_perm:[1,0,3,2] row_mask:0xf bank_mask:0xf
	s_nop 1
	v_add_f32_dpp v144, v144, v144 quad_perm:[2,3,0,1] row_mask:0xf bank_mask:0xf
	s_nop 1
	v_add_f32_dpp v144, v144, v144 row_half_mirror row_mask:0xf bank_mask:0xf
	s_nop 1
	v_add_f32_dpp v144, v144, v144 row_mirror row_mask:0xf bank_mask:0xf
	s_nop 0
	v_mov_b32_e32 v145, v144
	s_nop 1
	v_permlane16_swap_b32_e32 v145, v144
	s_nop 0
	v_add_f32_e32 v144, v144, v145
	v_mov_b32_e32 v145, v144
	s_nop 1
	v_permlane32_swap_b32_e32 v145, v144
	s_nop 0
	v_add_f32_e32 v144, v144, v145
	v_fma_f32 v146, v144, s6, v148
	v_rsq_f32_e32 v146, v146
	s_nop 0
	v_mov_b32_e32 v147, v146
	v_pk_mul_f32 v[0:1], v[0:1], v[146:147]
	v_pk_mul_f32 v[2:3], v[2:3], v[146:147]
	v_pk_mul_f32 v[4:5], v[4:5], v[146:147]
	v_pk_mul_f32 v[6:7], v[6:7], v[146:147]
	v_pk_mul_f32 v[8:9], v[8:9], v[146:147]
	v_pk_mul_f32 v[10:11], v[10:11], v[146:147]
	v_pk_mul_f32 v[12:13], v[12:13], v[146:147]
	v_pk_mul_f32 v[14:15], v[14:15], v[146:147]
	v_pk_mul_f32 v[16:17], v[16:17], v[146:147]
	v_pk_mul_f32 v[18:19], v[18:19], v[146:147]
	v_pk_mul_f32 v[20:21], v[20:21], v[146:147]
	v_pk_mul_f32 v[22:23], v[22:23], v[146:147]
	v_pk_mul_f32 v[24:25], v[24:25], v[146:147]
	v_pk_mul_f32 v[26:27], v[26:27], v[146:147]
	v_pk_mul_f32 v[28:29], v[28:29], v[146:147]
	v_pk_mul_f32 v[30:31], v[30:31], v[146:147]
	v_pk_fma_f32 v[0:1], v[0:1], v[64:65], v[96:97]
	v_pk_fma_f32 v[2:3], v[2:3], v[66:67], v[98:99]
	v_pk_fma_f32 v[4:5], v[4:5], v[68:69], v[100:101]
	v_pk_fma_f32 v[6:7], v[6:7], v[70:71], v[102:103]
	v_pk_fma_f32 v[8:9], v[8:9], v[72:73], v[104:105]
	v_pk_fma_f32 v[10:11], v[10:11], v[74:75], v[106:107]
	v_pk_fma_f32 v[12:13], v[12:13], v[76:77], v[108:109]
	v_pk_fma_f32 v[14:15], v[14:15], v[78:79], v[110:111]
	v_pk_fma_f32 v[16:17], v[16:17], v[80:81], v[112:113]
	v_pk_fma_f32 v[18:19], v[18:19], v[82:83], v[114:115]
	v_pk_fma_f32 v[20:21], v[20:21], v[84:85], v[116:117]
	v_pk_fma_f32 v[22:23], v[22:23], v[86:87], v[118:119]
	v_pk_fma_f32 v[24:25], v[24:25], v[88:89], v[120:121]
	v_pk_fma_f32 v[26:27], v[26:27], v[90:91], v[122:123]
	v_pk_fma_f32 v[28:29], v[28:29], v[92:93], v[124:125]
	v_pk_fma_f32 v[30:31], v[30:31], v[94:95], v[126:127]
	v_cvt_pk_bf16_f32 v128, v0, v1
	v_cvt_pk_bf16_f32 v129, v2, v3
	v_cvt_pk_bf16_f32 v130, v4, v5
	v_cvt_pk_bf16_f32 v131, v6, v7
	v_cvt_pk_bf16_f32 v132, v8, v9
	v_cvt_pk_bf16_f32 v133, v10, v11
	v_cvt_pk_bf16_f32 v134, v12, v13
	v_cvt_pk_bf16_f32 v135, v14, v15
	v_cvt_pk_bf16_f32 v136, v16, v17
	v_cvt_pk_bf16_f32 v137, v18, v19
	v_cvt_pk_bf16_f32 v138, v20, v21
	v_cvt_pk_bf16_f32 v139, v22, v23
	v_cvt_pk_bf16_f32 v140, v24, v25
	v_cvt_pk_bf16_f32 v141, v26, v27
	v_cvt_pk_bf16_f32 v142, v28, v29
	v_cvt_pk_bf16_f32 v143, v30, v31
	global_store_dwordx2 v151, v[128:129], s[18:19]
	global_store_dwordx2 v151, v[130:131], s[18:19] offset:512
	global_store_dwordx2 v151, v[132:133], s[18:19] offset:1024
	global_store_dwordx2 v151, v[134:135], s[18:19] offset:1536
	global_store_dwordx2 v151, v[136:137], s[18:19] offset:2048
	global_store_dwordx2 v151, v[138:139], s[18:19] offset:2560
	global_store_dwordx2 v151, v[140:141], s[18:19] offset:3072
	global_store_dwordx2 v151, v[142:143], s[18:19] offset:3584
	s_add_u32 s18, s18, 0x1000
	s_addc_u32 s19, s19, 0
	global_load_dwordx4 v[0:3], v149, s[12:13]
	global_load_dwordx4 v[4:7], v149, s[12:13] offset:1024
	global_load_dwordx4 v[8:11], v149, s[12:13] offset:2048
	global_load_dwordx4 v[12:15], v149, s[12:13] offset:3072
	global_load_dwordx4 v[16:19], v150, s[12:13]
	global_load_dwordx4 v[20:23], v150, s[12:13] offset:1024
	global_load_dwordx4 v[24:27], v150, s[12:13] offset:2048
	global_load_dwordx4 v[28:31], v150, s[12:13] offset:3072
	s_add_u32 s12, s12, 0x2000
	s_addc_u32 s13, s13, 0
	s_waitcnt vmcnt(16)
; DI unsigned pk2(float lo, float hi) { f32x2 v = {lo, hi}; bf16x2n b = __builtin_convertvector(v, bf16x2n); return __builtin_bit_cast(unsigned, b); }
; DI void norm_phase(const int wv, const float* xin, const float* gvec, const float* sh, const float* sc, bf16_t* hout) {
;     ...
;         float s = 0.f;
; #pragma unroll
;         for (int j = 0; j < 8; ++j) s += (v[j].x * v[j].x + v[j].y * v[j].y) + (v[j].z * v[j].z + v[j].w * v[j].w);
; #pragma unroll
;         for (int o = 1; o < 64; o <<= 1) s += __shfl_xor(s, o);
;         const float rstd = rsqrtf(s * (1.f / D) + 1e-6f);
;         u32x2* o8 = (u32x2*)(hout + (size_t)m * D) + lane;
; #pragma unroll
;         for (int j = 0; j < 8; ++j) { const f32x4 y = v[j] * rstd * gp[j] + hh[j];
;             u32x2 w; w.x = pk2(y.x, y.y); w.y = pk2(y.z, y.w); o8[64 * j] = w; }
; #pragma unroll
;         for (int j = 0; j < 8; ++j) v[j] = vn[j];
;     }
	v_pk_mul_f32 v[152:153], v[32:33], v[32:33]
	v_pk_fma_f32 v[152:153], v[34:35], v[34:35], v[152:153]
	v_pk_fma_f32 v[152:153], v[36:37], v[36:37], v[152:153]
	v_pk_fma_f32 v[152:153], v[38:39], v[38:39], v[152:153]
	v_pk_fma_f32 v[152:153], v[40:41], v[40:41], v[152:153]
	v_pk_fma_f32 v[152:153], v[42:43], v[42:43], v[152:153]
	v_pk_fma_f32 v[152:153], v[44:45], v[44:45], v[152:153]
	v_pk_fma_f32 v[152:153], v[46:47], v[46:47], v[152:153]
	v_pk_fma_f32 v[152:153], v[48:49], v[48:49], v[152:153]
	v_pk_fma_f32 v[152:153], v[50:51], v[50:51], v[152:153]
	v_pk_fma_f32 v[152:153], v[52:53], v[52:53], v[152:153]
	v_pk_fma_f32 v[152:153], v[54:55], v[54:55], v[152:153]
	v_pk_fma_f32 v[152:153], v[56:57], v[56:57], v[152:153]
	v_pk_fma_f32 v[152:153], v[58:59], v[58:59], v[152:153]
	v_pk_fma_f32 v[152:153], v[60:61], v[60:61], v[152:153]
	v_pk_fma_f32 v[152:153], v[62:63], v[62:63], v[152:153]
	s_nop 0
	v_add_f32_e32 v144, v152, v153
	s_nop 1
	v_add_f32_dpp v144, v144, v144 quad_perm:[1,0,3,2] row_mask:0xf bank_mask:0xf
	s_nop 1
	v_add_f32_dpp v144, v144, v144 quad_perm:[2,3,0,1] row_mask:0xf bank_mask:0xf
	s_nop 1
	v_add_f32_dpp v144, v144, v144 row_half_mirror row_mask:0xf bank_mask:0xf
	s_nop 1
	v_add_f32_dpp v144, v144, v144 row_mirror row_mask:0xf bank_mask:0xf
	s_nop 0
	v_mov_b32_e32 v145, v144
	s_nop 1
	v_permlane16_swap_b32_e32 v145, v144
	s_nop 0
	v_add_f32_e32 v144, v144, v145
	v_mov_b32_e32 v145, v144
	s_nop 1
	v_permlane32_swap_b32_e32 v145, v144
	s_nop 0
	v_add_f32_e32 v144, v144, v145
	v_fma_f32 v146, v144, s6, v148
	v_rsq_f32_e32 v146, v146
	s_nop 0
	v_mov_b32_e32 v147, v146
	v_pk_mul_f32 v[32:33], v[32:33], v[146:147]
	v_pk_mul_f32 v[34:35], v[34:35], v[146:147]
	v_pk_mul_f32 v[36:37], v[36:37], v[146:147]
	v_pk_mul_f32 v[38:39], v[38:39], v[146:147]
	v_pk_mul_f32 v[40:41], v[40:41], v[146:147]
	v_pk_mul_f32 v[42:43], v[42:43], v[146:147]
	v_pk_mul_f32 v[44:45], v[44:45], v[146:147]
	v_pk_mul_f32 v[46:47], v[46:47], v[146:147]
	v_pk_mul_f32 v[48:49], v[48:49], v[146:147]
	v_pk_mul_f32 v[50:51], v[50:51], v[146:147]
	v_pk_mul_f32 v[52:53], v[52:53], v[146:147]
	v_pk_mul_f32 v[54:55], v[54:55], v[146:147]
	v_pk_mul_f32 v[56:57], v[56:57], v[146:147]
	v_pk_mul_f32 v[58:59], v[58:59], v[146:147]
	v_pk_mul_f32 v[60:61], v[60:61], v[146:147]
	v_pk_mul_f32 v[62:63], v[62:63], v[146:147]
	v_pk_fma_f32 v[32:33], v[32:33], v[64:65], v[96:97]
	v_pk_fma_f32 v[34:35], v[34:35], v[66:67], v[98:99]
	v_pk_fma_f32 v[36:37], v[36:37], v[68:69], v[100:101]
	v_pk_fma_f32 v[38:39], v[38:39], v[70:71], v[102:103]
	v_pk_fma_f32 v[40:41], v[40:41], v[72:73], v[104:105]
	v_pk_fma_f32 v[42:43], v[42:43], v[74:75], v[106:107]
	v_pk_fma_f32 v[44:45], v[44:45], v[76:77], v[108:109]
	v_pk_fma_f32 v[46:47], v[46:47], v[78:79], v[110:111]
	v_pk_fma_f32 v[48:49], v[48:49], v[80:81], v[112:113]
	v_pk_fma_f32 v[50:51], v[50:51], v[82:83], v[114:115]
	v_pk_fma_f32 v[52:53], v[52:53], v[84:85], v[116:117]
	v_pk_fma_f32 v[54:55], v[54:55], v[86:87], v[118:119]
	v_pk_fma_f32 v[56:57], v[56:57], v[88:89], v[120:121]
	v_pk_fma_f32 v[58:59], v[58:59], v[90:91], v[122:123]
	v_pk_fma_f32 v[60:61], v[60:61], v[92:93], v[124:125]
	v_pk_fma_f32 v[62:63], v[62:63], v[94:95], v[126:127]
	v_cvt_pk_bf16_f32 v128, v32, v33
	v_cvt_pk_bf16_f32 v129, v34, v35
	v_cvt_pk_bf16_f32 v130, v36, v37
	v_cvt_pk_bf16_f32 v131, v38, v39
	v_cvt_pk_bf16_f32 v132, v40, v41
	v_cvt_pk_bf16_f32 v133, v42, v43
	v_cvt_pk_bf16_f32 v134, v44, v45
	v_cvt_pk_bf16_f32 v135, v46, v47
	v_cvt_pk_bf16_f32 v136, v48, v49
	v_cvt_pk_bf16_f32 v137, v50, v51
	v_cvt_pk_bf16_f32 v138, v52, v53
	v_cvt_pk_bf16_f32 v139, v54, v55
	v_cvt_pk_bf16_f32 v140, v56, v57
	v_cvt_pk_bf16_f32 v141, v58, v59
	v_cvt_pk_bf16_f32 v142, v60, v61
	v_cvt_pk_bf16_f32 v143, v62, v63
	global_store_dwordx2 v151, v[128:129], s[18:19]
	global_store_dwordx2 v151, v[130:131], s[18:19] offset:512
	global_store_dwordx2 v151, v[132:133], s[18:19] offset:1024
	global_store_dwordx2 v151, v[134:135], s[18:19] offset:1536
	global_store_dwordx2 v151, v[136:137], s[18:19] offset:2048
	global_store_dwordx2 v151, v[138:139], s[18:19] offset:2560
	global_store_dwordx2 v151, v[140:141], s[18:19] offset:3072
	global_store_dwordx2 v151, v[142:143], s[18:19] offset:3584
	s_add_u32 s18, s18, 0x1000
	s_addc_u32 s19, s19, 0
	global_load_dwordx4 v[32:35], v149, s[12:13]
	global_load_dwordx4 v[36:39], v149, s[12:13] offset:1024
	global_load_dwordx4 v[40:43], v149, s[12:13] offset:2048
	global_load_dwordx4 v[44:47], v149, s[12:13] offset:3072
	global_load_dwordx4 v[48:51], v150, s[12:13]
	global_load_dwordx4 v[52:55], v150, s[12:13] offset:1024
	global_load_dwordx4 v[56:59], v150, s[12:13] offset:2048
	global_load_dwordx4 v[60:63], v150, s[12:13] offset:3072
	s_add_u32 s12, s12, 0x2000
	s_addc_u32 s13, s13, 0
	s_waitcnt vmcnt(16)
; DI unsigned pk2(float lo, float hi) { f32x2 v = {lo, hi}; bf16x2n b = __builtin_convertvector(v, bf16x2n); return __builtin_bit_cast(unsigned, b); }
; DI void norm_phase(const int wv, const float* xin, const float* gvec, const float* sh, const float* sc, bf16_t* hout) {
;     ...
;         float s = 0.f;
; #pragma unroll
;         for (int j = 0; j < 8; ++j) s += (v[j].x * v[j].x + v[j].y * v[j].y) + (v[j].z * v[j].z + v[j].w * v[j].w);
; #pragma unroll
;         for (int o = 1; o < 64; o <<= 1) s += __shfl_xor(s, o);
;         const float rstd = rsqrtf(s * (1.f / D) + 1e-6f);
;         u32x2* o8 = (u32x2*)(hout + (size_t)m * D) + lane;
; #pragma unroll
;         for (int j = 0; j < 8; ++j) { const f32x4 y = v[j] * rstd * gp[j] + hh[j];
;             u32x2 w; w.x = pk2(y.x, y.y); w.y = pk2(y.z, y.w); o8[64 * j] = w; }
; #pragma unroll
;         for (int j = 0; j < 8; ++j) v[j] = vn[j];
;     }
	v_pk_mul_f32 v[152:153], v[0:1], v[0:1]
	v_pk_fma_f32 v[152:153], v[2:3], v[2:3], v[152:153]
	v_pk_fma_f32 v[152:153], v[4:5], v[4:5], v[152:153]
	v_pk_fma_f32 v[152:153], v[6:7], v[6:7], v[152:153]
	v_pk_fma_f32 v[152:153], v[8:9], v[8:9], v[152:153]
	v_pk_fma_f32 v[152:153], v[10:11], v[10:11], v[152:153]
	v_pk_fma_f32 v[152:153], v[12:13], v[12:13], v[152:153]
	v_pk_fma_f32 v[152:153], v[14:15], v[14:15], v[152:153]
	v_pk_fma_f32 v[152:153], v[16:17], v[16:17], v[152:153]
	v_pk_fma_f32 v[152:153], v[18:19], v[18:19], v[152:153]
	v_pk_fma_f32 v[152:153], v[20:21], v[20:21], v[152:153]
	v_pk_fma_f32 v[152:153], v[22:23], v[22:23], v[152:153]
	v_pk_fma_f32 v[152:153], v[24:25], v[24:25], v[152:153]
	v_pk_fma_f32 v[152:153], v[26:27], v[26:27], v[152:153]
	v_pk_fma_f32 v[152:153], v[28:29], v[28:29], v[152:153]
	v_pk_fma_f32 v[152:153], v[30:31], v[30:31], v[152:153]
	s_nop 0
	v_add_f32_e32 v144, v152, v153
	s_nop 1
	v_add_f32_dpp v144, v144, v144 quad_perm:[1,0,3,2] row_mask:0xf bank_mask:0xf
	s_nop 1
	v_add_f32_dpp v144, v144, v144 quad_perm:[2,3,0,1] row_mask:0xf bank_mask:0xf
	s_nop 1
	v_add_f32_dpp v144, v144, v144 row_half_mirror row_mask:0xf bank_mask:0xf
	s_nop 1
	v_add_f32_dpp v144, v144, v144 row_mirror row_mask:0xf bank_mask:0xf
	s_nop 0
	v_mov_b32_e32 v145, v144
	s_nop 1
	v_permlane16_swap_b32_e32 v145, v144
	s_nop 0
	v_add_f32_e32 v144, v144, v145
	v_mov_b32_e32 v145, v144
	s_nop 1
	v_permlane32_swap_b32_e32 v145, v144
	s_nop 0
	v_add_f32_e32 v144, v144, v145
	v_fma_f32 v146, v144, s6, v148
	v_rsq_f32_e32 v146, v146
	s_nop 0
	v_mov_b32_e32 v147, v146
	v_pk_mul_f32 v[0:1], v[0:1], v[146:147]
	v_pk_mul_f32 v[2:3], v[2:3], v[146:147]
	v_pk_mul_f32 v[4:5], v[4:5], v[146:147]
	v_pk_mul_f32 v[6:7], v[6:7], v[146:147]
	v_pk_mul_f32 v[8:9], v[8:9], v[146:147]
	v_pk_mul_f32 v[10:11], v[10:11], v[146:147]
	v_pk_mul_f32 v[12:13], v[12:13], v[146:147]
	v_pk_mul_f32 v[14:15], v[14:15], v[146:147]
	v_pk_mul_f32 v[16:17], v[16:17], v[146:147]
	v_pk_mul_f32 v[18:19], v[18:19], v[146:147]
	v_pk_mul_f32 v[20:21], v[20:21], v[146:147]
	v_pk_mul_f32 v[22:23], v[22:23], v[146:147]
	v_pk_mul_f32 v[24:25], v[24:25], v[146:147]
	v_pk_mul_f32 v[26:27], v[26:27], v[146:147]
	v_pk_mul_f32 v[28:29], v[28:29], v[146:147]
	v_pk_mul_f32 v[30:31], v[30:31], v[146:147]
	v_pk_fma_f32 v[0:1], v[0:1], v[64:65], v[96:97]
	v_pk_fma_f32 v[2:3], v[2:3], v[66:67], v[98:99]
	v_pk_fma_f32 v[4:5], v[4:5], v[68:69], v[100:101]
	v_pk_fma_f32 v[6:7], v[6:7], v[70:71], v[102:103]
	v_pk_fma_f32 v[8:9], v[8:9], v[72:73], v[104:105]
	v_pk_fma_f32 v[10:11], v[10:11], v[74:75], v[106:107]
	v_pk_fma_f32 v[12:13], v[12:13], v[76:77], v[108:109]
	v_pk_fma_f32 v[14:15], v[14:15], v[78:79], v[110:111]
	v_pk_fma_f32 v[16:17], v[16:17], v[80:81], v[112:113]
	v_pk_fma_f32 v[18:19], v[18:19], v[82:83], v[114:115]
	v_pk_fma_f32 v[20:21], v[20:21], v[84:85], v[116:117]
	v_pk_fma_f32 v[22:23], v[22:23], v[86:87], v[118:119]
	v_pk_fma_f32 v[24:25], v[24:25], v[88:89], v[120:121]
	v_pk_fma_f32 v[26:27], v[26:27], v[90:91], v[122:123]
	v_pk_fma_f32 v[28:29], v[28:29], v[92:93], v[124:125]
	v_pk_fma_f32 v[30:31], v[30:31], v[94:95], v[126:127]
	v_cvt_pk_bf16_f32 v128, v0, v1
	v_cvt_pk_bf16_f32 v129, v2, v3
	v_cvt_pk_bf16_f32 v130, v4, v5
	v_cvt_pk_bf16_f32 v131, v6, v7
	v_cvt_pk_bf16_f32 v132, v8, v9
	v_cvt_pk_bf16_f32 v133, v10, v11
	v_cvt_pk_bf16_f32 v134, v12, v13
	v_cvt_pk_bf16_f32 v135, v14, v15
	v_cvt_pk_bf16_f32 v136, v16, v17
	v_cvt_pk_bf16_f32 v137, v18, v19
	v_cvt_pk_bf16_f32 v138, v20, v21
	v_cvt_pk_bf16_f32 v139, v22, v23
	v_cvt_pk_bf16_f32 v140, v24, v25
	v_cvt_pk_bf16_f32 v141, v26, v27
	v_cvt_pk_bf16_f32 v142, v28, v29
	v_cvt_pk_bf16_f32 v143, v30, v31
	global_store_dwordx2 v151, v[128:129], s[18:19]
	global_store_dwordx2 v151, v[130:131], s[18:19] offset:512
	global_store_dwordx2 v151, v[132:133], s[18:19] offset:1024
	global_store_dwordx2 v151, v[134:135], s[18:19] offset:1536
	global_store_dwordx2 v151, v[136:137], s[18:19] offset:2048
	global_store_dwordx2 v151, v[138:139], s[18:19] offset:2560
	global_store_dwordx2 v151, v[140:141], s[18:19] offset:3072
	global_store_dwordx2 v151, v[142:143], s[18:19] offset:3584
	s_add_u32 s18, s18, 0x1000
	s_addc_u32 s19, s19, 0
	s_waitcnt vmcnt(8)
; DI unsigned pk2(float lo, float hi) { f32x2 v = {lo, hi}; bf16x2n b = __builtin_convertvector(v, bf16x2n); return __builtin_bit_cast(unsigned, b); }
; DI void norm_phase(const int wv, const float* xin, const float* gvec, const float* sh, const float* sc, bf16_t* hout) {
;     ...
;         float s = 0.f;
; #pragma unroll
;         for (int j = 0; j < 8; ++j) s += (v[j].x * v[j].x + v[j].y * v[j].y) + (v[j].z * v[j].z + v[j].w * v[j].w);
; #pragma unroll
;         for (int o = 1; o < 64; o <<= 1) s += __shfl_xor(s, o);
;         const float rstd = rsqrtf(s * (1.f / D) + 1e-6f);
;         u32x2* o8 = (u32x2*)(hout + (size_t)m * D) + lane;
; #pragma unroll
;         for (int j = 0; j < 8; ++j) { const f32x4 y = v[j] * rstd * gp[j] + hh[j];
;             u32x2 w; w.x = pk2(y.x, y.y); w.y = pk2(y.z, y.w); o8[64 * j] = w; }
; #pragma unroll
;         for (int j = 0; j < 8; ++j) v[j] = vn[j];
;     }
	v_pk_mul_f32 v[152:153], v[32:33], v[32:33]
	v_pk_fma_f32 v[152:153], v[34:35], v[34:35], v[152:153]
	v_pk_fma_f32 v[152:153], v[36:37], v[36:37], v[152:153]
	v_pk_fma_f32 v[152:153], v[38:39], v[38:39], v[152:153]
	v_pk_fma_f32 v[152:153], v[40:41], v[40:41], v[152:153]
	v_pk_fma_f32 v[152:153], v[42:43], v[42:43], v[152:153]
	v_pk_fma_f32 v[152:153], v[44:45], v[44:45], v[152:153]
	v_pk_fma_f32 v[152:153], v[46:47], v[46:47], v[152:153]
	v_pk_fma_f32 v[152:153], v[48:49], v[48:49], v[152:153]
	v_pk_fma_f32 v[152:153], v[50:51], v[50:51], v[152:153]
	v_pk_fma_f32 v[152:153], v[52:53], v[52:53], v[152:153]
	v_pk_fma_f32 v[152:153], v[54:55], v[54:55], v[152:153]
	v_pk_fma_f32 v[152:153], v[56:57], v[56:57], v[152:153]
	v_pk_fma_f32 v[152:153], v[58:59], v[58:59], v[152:153]
	v_pk_fma_f32 v[152:153], v[60:61], v[60:61], v[152:153]
	v_pk_fma_f32 v[152:153], v[62:63], v[62:63], v[152:153]
	s_nop 0
	v_add_f32_e32 v144, v152, v153
	s_nop 1
	v_add_f32_dpp v144, v144, v144 quad_perm:[1,0,3,2] row_mask:0xf bank_mask:0xf
	s_nop 1
	v_add_f32_dpp v144, v144, v144 quad_perm:[2,3,0,1] row_mask:0xf bank_mask:0xf
	s_nop 1
	v_add_f32_dpp v144, v144, v144 row_half_mirror row_mask:0xf bank_mask:0xf
	s_nop 1
	v_add_f32_dpp v144, v144, v144 row_mirror row_mask:0xf bank_mask:0xf
	s_nop 0
	v_mov_b32_e32 v145, v144
	s_nop 1
	v_permlane16_swap_b32_e32 v145, v144
	s_nop 0
	v_add_f32_e32 v144, v144, v145
	v_mov_b32_e32 v145, v144
	s_nop 1
	v_permlane32_swap_b32_e32 v145, v144
	s_nop 0
	v_add_f32_e32 v144, v144, v145
	v_fma_f32 v146, v144, s6, v148
	v_rsq_f32_e32 v146, v146
	s_nop 0
	v_mov_b32_e32 v147, v146
	v_pk_mul_f32 v[32:33], v[32:33], v[146:147]
	v_pk_mul_f32 v[34:35], v[34:35], v[146:147]
	v_pk_mul_f32 v[36:37], v[36:37], v[146:147]
	v_pk_mul_f32 v[38:39], v[38:39], v[146:147]
	v_pk_mul_f32 v[40:41], v[40:41], v[146:147]
	v_pk_mul_f32 v[42:43], v[42:43], v[146:147]
	v_pk_mul_f32 v[44:45], v[44:45], v[146:147]
	v_pk_mul_f32 v[46:47], v[46:47], v[146:147]
	v_pk_mul_f32 v[48:49], v[48:49], v[146:147]
	v_pk_mul_f32 v[50:51], v[50:51], v[146:147]
	v_pk_mul_f32 v[52:53], v[52:53], v[146:147]
	v_pk_mul_f32 v[54:55], v[54:55], v[146:147]
	v_pk_mul_f32 v[56:57], v[56:57], v[146:147]
	v_pk_mul_f32 v[58:59], v[58:59], v[146:147]
	v_pk_mul_f32 v[60:61], v[60:61], v[146:147]
	v_pk_mul_f32 v[62:63], v[62:63], v[146:147]
	v_pk_fma_f32 v[32:33], v[32:33], v[64:65], v[96:97]
	v_pk_fma_f32 v[34:35], v[34:35], v[66:67], v[98:99]
	v_pk_fma_f32 v[36:37], v[36:37], v[68:69], v[100:101]
	v_pk_fma_f32 v[38:39], v[38:39], v[70:71], v[102:103]
	v_pk_fma_f32 v[40:41], v[40:41], v[72:73], v[104:105]
	v_pk_fma_f32 v[42:43], v[42:43], v[74:75], v[106:107]
	v_pk_fma_f32 v[44:45], v[44:45], v[76:77], v[108:109]
	v_pk_fma_f32 v[46:47], v[46:47], v[78:79], v[110:111]
	v_pk_fma_f32 v[48:49], v[48:49], v[80:81], v[112:113]
	v_pk_fma_f32 v[50:51], v[50:51], v[82:83], v[114:115]
	v_pk_fma_f32 v[52:53], v[52:53], v[84:85], v[116:117]
	v_pk_fma_f32 v[54:55], v[54:55], v[86:87], v[118:119]
	v_pk_fma_f32 v[56:57], v[56:57], v[88:89], v[120:121]
	v_pk_fma_f32 v[58:59], v[58:59], v[90:91], v[122:123]
	v_pk_fma_f32 v[60:61], v[60:61], v[92:93], v[124:125]
	v_pk_fma_f32 v[62:63], v[62:63], v[94:95], v[126:127]
	v_cvt_pk_bf16_f32 v128, v32, v33
	v_cvt_pk_bf16_f32 v129, v34, v35
	v_cvt_pk_bf16_f32 v130, v36, v37
	v_cvt_pk_bf16_f32 v131, v38, v39
	v_cvt_pk_bf16_f32 v132, v40, v41
	v_cvt_pk_bf16_f32 v133, v42, v43
	v_cvt_pk_bf16_f32 v134, v44, v45
	v_cvt_pk_bf16_f32 v135, v46, v47
	v_cvt_pk_bf16_f32 v136, v48, v49
	v_cvt_pk_bf16_f32 v137, v50, v51
	v_cvt_pk_bf16_f32 v138, v52, v53
	v_cvt_pk_bf16_f32 v139, v54, v55
	v_cvt_pk_bf16_f32 v140, v56, v57
	v_cvt_pk_bf16_f32 v141, v58, v59
	v_cvt_pk_bf16_f32 v142, v60, v61
	v_cvt_pk_bf16_f32 v143, v62, v63
	global_store_dwordx2 v151, v[128:129], s[18:19]
	global_store_dwordx2 v151, v[130:131], s[18:19] offset:512
	global_store_dwordx2 v151, v[132:133], s[18:19] offset:1024
	global_store_dwordx2 v151, v[134:135], s[18:19] offset:1536
	global_store_dwordx2 v151, v[136:137], s[18:19] offset:2048
	global_store_dwordx2 v151, v[138:139], s[18:19] offset:2560
	global_store_dwordx2 v151, v[140:141], s[18:19] offset:3072
	global_store_dwordx2 v151, v[142:143], s[18:19] offset:3584
	s_add_u32 s18, s18, 0x1000
	s_addc_u32 s19, s19, 0
	v_readlane_b32 s12, v253, 0
	v_readlane_b32 s13, v253, 1
	v_readlane_b32 s14, v253, 2
	v_readlane_b32 s15, v253, 3
	v_readlane_b32 s16, v253, 4
	v_readlane_b32 s17, v253, 5
	v_readlane_b32 s18, v253, 6
	v_readlane_b32 s19, v253, 7
	v_readlane_b32 s20, v253, 8
	v_readlane_b32 s21, v253, 9
	v_readlane_b32 s22, v253, 10
	v_readlane_b32 s23, v253, 11
	v_readlane_b32 s24, v253, 12
	v_readlane_b32 s25, v253, 13
	v_readlane_b32 s26, v253, 14
	v_readlane_b32 s27, v253, 15
	v_readlane_b32 s8, v253, 24
	v_readlane_b32 s29, v254, 59
	s_movk_i32 s28, 0x100
	s_movk_i32 s4, 0x1000
	s_mov_b32 s5, 0x800000
	s_mov_b32 s6, 0x3a000000
	s_mov_b32 s7, 0
	s_mov_b32 s11, s87
	v_lshrrev_b32_e32 v160, 0, v149
	s_nop 3

; template <int MODE> ...
;     ...
;         ATT_SOFTMAX(X0, 0);
;         if (MODE >= 2) ATT_PV(X0, 0);
;         ATT_SOFTMAX(X1, 1);
;         if (MODE >= 2) ATT_PV(X1, 1);
.LBB0_587:
	v_add_u32_e32 v96, s19, v232
	v_add_u32_e32 v99, v96, v233
	v_add_u32_e32 v96, 0x4000, v99
	v_add_u32_e32 v97, 0x5000, v99
	v_add_u32_e32 v98, 0x6000, v99
	v_add_u32_e32 v99, 0x7000, v99
	ds_read2_b64 v[240:243], v96 offset0:128 offset1:130
	ds_read2_b64 v[244:247], v97 offset0:160 offset1:162
	ds_read2_b64 v[248:251], v98 offset0:192 offset1:194
	v_cvt_pk_bf16_f32 v80, v80, v81
	v_cvt_pk_bf16_f32 v81, v82, v83
	v_cvt_pk_bf16_f32 v82, v84, v85
	v_cvt_pk_bf16_f32 v83, v86, v87
	ds_read2_b64 v[84:87], v99 offset0:224 offset1:226
	ds_read2_b64 v[100:103], v96 offset0:132 offset1:134
	v_exp_f32_e32 v64, v64
	v_exp_f32_e32 v65, v65
	v_exp_f32_e32 v66, v66
	v_exp_f32_e32 v67, v67
	s_waitcnt lgkmcnt(4)
	v_mfma_f32_32x32x16_bf16 v[48:63], v[240:243], v[80:83], v[48:63]
	ds_read2_b64 v[240:243], v97 offset0:164 offset1:166
	v_exp_f32_e32 v68, v68
	v_exp_f32_e32 v69, v69
	v_exp_f32_e32 v70, v70
	s_waitcnt lgkmcnt(4)
	v_mfma_f32_32x32x16_bf16 v[32:47], v[244:247], v[80:83], v[32:47]
	ds_read2_b64 v[244:247], v98 offset0:196 offset1:198
	v_exp_f32_e32 v71, v71
	v_exp_f32_e32 v72, v72
	v_exp_f32_e32 v73, v73
	s_waitcnt lgkmcnt(4)
	v_mfma_f32_32x32x16_bf16 v[16:31], v[248:251], v[80:83], v[16:31]
	ds_read2_b64 v[248:251], v99 offset0:228 offset1:230
	v_exp_f32_e32 v74, v74
	v_exp_f32_e32 v75, v75
	v_exp_f32_e32 v76, v76
	s_waitcnt lgkmcnt(4)
	v_mfma_f32_32x32x16_bf16 v[0:15], v[84:87], v[80:83], v[0:15]
	v_exp_f32_e32 v77, v77
	v_exp_f32_e32 v78, v78
	v_exp_f32_e32 v79, v79
	v_cvt_pk_bf16_f32 v80, v88, v89
	v_cvt_pk_bf16_f32 v81, v90, v91
	v_cvt_pk_bf16_f32 v82, v92, v93
	v_cvt_pk_bf16_f32 v83, v94, v95
	s_mov_b64 s[10:11], -1
	s_andn2_b64 vcc, exec, s[8:9]
	s_waitcnt lgkmcnt(3)
	v_mfma_f32_32x32x16_bf16 v[48:63], v[100:103], v[80:83], v[48:63]
	s_waitcnt lgkmcnt(2)
	v_mfma_f32_32x32x16_bf16 v[32:47], v[240:243], v[80:83], v[32:47]
	ds_read2_b64 v[240:243], v96 offset0:136 offset1:138
	s_waitcnt lgkmcnt(2)
	v_mfma_f32_32x32x16_bf16 v[16:31], v[244:247], v[80:83], v[16:31]
	ds_read2_b64 v[244:247], v97 offset0:168 offset1:170
	s_waitcnt lgkmcnt(2)
	v_mfma_f32_32x32x16_bf16 v[0:15], v[248:251], v[80:83], v[0:15]
	ds_read2_b64 v[248:251], v98 offset0:200 offset1:202
	s_cbranch_vccnz .LBB0_589
	v_cmp_lt_i32_e32 vcc, 31, v235
	s_and_b64 vcc, vcc, s[2:3]
	s_mov_b64 s[10:11], 0
	v_cndmask_b32_e32 v80, 0, v64, vcc
	v_cmp_lt_i32_e32 vcc, 32, v235
	s_and_b64 vcc, vcc, s[2:3]
	v_add_f32_e32 v82, v80, v236
	v_cndmask_b32_e32 v81, 0, v65, vcc
	v_cmp_lt_i32_e32 vcc, 33, v235
	s_and_b64 vcc, vcc, s[2:3]
	v_add_f32_e32 v83, v81, v82
	v_cndmask_b32_e32 v82, 0, v66, vcc
	v_cmp_lt_i32_e32 vcc, 34, v235
	s_and_b64 vcc, vcc, s[2:3]
	v_add_f32_e32 v84, v82, v83
	v_cndmask_b32_e32 v83, 0, v67, vcc
	v_cmp_lt_i32_e32 vcc, 39, v235
	s_and_b64 vcc, vcc, s[2:3]
	v_add_f32_e32 v85, v83, v84
	v_cndmask_b32_e32 v84, 0, v68, vcc
	v_cmp_lt_i32_e32 vcc, 40, v235
	s_and_b64 vcc, vcc, s[2:3]
	v_add_f32_e32 v86, v84, v85
	v_cndmask_b32_e32 v85, 0, v69, vcc
	v_cmp_lt_i32_e32 vcc, 41, v235
	s_and_b64 vcc, vcc, s[2:3]
	v_add_f32_e32 v87, v85, v86
	v_cndmask_b32_e32 v86, 0, v70, vcc
	v_cmp_lt_i32_e32 vcc, 42, v235
	s_and_b64 vcc, vcc, s[2:3]
	v_add_f32_e32 v88, v86, v87
	v_cndmask_b32_e32 v87, 0, v71, vcc
	v_cmp_lt_i32_e32 vcc, 47, v235
	s_and_b64 vcc, vcc, s[2:3]
	v_add_f32_e32 v89, v87, v88
	v_cndmask_b32_e32 v88, 0, v72, vcc
	v_cmp_lt_i32_e32 vcc, 48, v235
	s_and_b64 vcc, vcc, s[2:3]
	v_add_f32_e32 v90, v88, v89
	v_cndmask_b32_e32 v89, 0, v73, vcc
	v_cmp_lt_i32_e32 vcc, 49, v235
	s_and_b64 vcc, vcc, s[2:3]
	v_add_f32_e32 v91, v89, v90
	v_cndmask_b32_e32 v90, 0, v74, vcc
	v_cmp_lt_i32_e32 vcc, 50, v235
	s_and_b64 vcc, vcc, s[2:3]
	v_add_f32_e32 v92, v90, v91
	v_cndmask_b32_e32 v91, 0, v75, vcc
	v_cmp_lt_i32_e32 vcc, 55, v235
	s_and_b64 vcc, vcc, s[2:3]
	v_add_f32_e32 v93, v91, v92
	v_cndmask_b32_e32 v92, 0, v76, vcc
	v_cmp_lt_i32_e32 vcc, 56, v235
	s_and_b64 vcc, vcc, s[2:3]
	v_add_f32_e32 v94, v92, v93
	v_cndmask_b32_e32 v93, 0, v77, vcc
	v_cmp_lt_i32_e32 vcc, 57, v235
	s_and_b64 vcc, vcc, s[2:3]
	v_add_f32_e32 v95, v93, v94
	v_cndmask_b32_e32 v94, 0, v78, vcc
	v_cmp_lt_i32_e32 vcc, 58, v235
	s_and_b64 vcc, vcc, s[2:3]
	v_add_f32_e32 v100, v94, v95
	v_cndmask_b32_e32 v95, 0, v79, vcc
	v_add_f32_e32 v100, v95, v100

; template <int MODE> ...
;     ...
;         ATT_SOFTMAX(X0, 0);
;         if (MODE >= 2) ATT_PV(X0, 0);
;         ATT_SOFTMAX(X1, 1);
;         if (MODE >= 2) ATT_PV(X1, 1);
;         if (MODE != 1) l_run += rs;
.LBB0_591:
	ds_read2_b64 v[64:67], v99 offset0:232 offset1:234
	ds_read2_b64 v[72:75], v96 offset0:140 offset1:142
	ds_read2_b64 v[76:79], v97 offset0:172 offset1:174
	v_cvt_pk_bf16_f32 v68, v80, v81
	v_cvt_pk_bf16_f32 v69, v82, v83
	v_cvt_pk_bf16_f32 v70, v84, v85
	v_cvt_pk_bf16_f32 v71, v86, v87
	v_add_f32_e32 v193, v193, v100
	s_waitcnt lgkmcnt(5)
	v_mfma_f32_32x32x16_bf16 v[48:63], v[240:243], v[68:71], v[48:63]
	s_waitcnt lgkmcnt(4)
	v_mfma_f32_32x32x16_bf16 v[32:47], v[244:247], v[68:71], v[32:47]
	ds_read2_b64 v[240:243], v98 offset0:204 offset1:206
	s_waitcnt lgkmcnt(4)
	v_mfma_f32_32x32x16_bf16 v[16:31], v[248:251], v[68:71], v[16:31]
	ds_read2_b64 v[244:247], v99 offset0:236 offset1:238
	s_waitcnt lgkmcnt(4)
	v_mfma_f32_32x32x16_bf16 v[0:15], v[64:67], v[68:71], v[0:15]
	v_cvt_pk_bf16_f32 v68, v88, v89
	v_cvt_pk_bf16_f32 v69, v90, v91
	v_cvt_pk_bf16_f32 v70, v92, v93
	v_cvt_pk_bf16_f32 v71, v94, v95
	s_waitcnt lgkmcnt(3)
	s_nop 0
	v_mfma_f32_32x32x16_bf16 v[48:63], v[72:75], v[68:71], v[48:63]
	s_waitcnt lgkmcnt(2)
	v_mfma_f32_32x32x16_bf16 v[32:47], v[76:79], v[68:71], v[32:47]
	s_waitcnt lgkmcnt(1)
	v_mfma_f32_32x32x16_bf16 v[16:31], v[240:243], v[68:71], v[16:31]
	s_waitcnt lgkmcnt(0)
	v_mfma_f32_32x32x16_bf16 v[0:15], v[244:247], v[68:71], v[0:15]
	s_andn2_b64 vcc, exec, s[6:7]
	s_cbranch_vccz .LBB0_594
	s_branch .LBB0_579
